# neighbourhood attention tile 0: counted vmcnt(11) instead of vmcnt(0) before the first QK MFMA; dead compares at the end of the PV phases removed
# baseline (speedup 1.0000x reference)
.LBB0_302:
	s_addk_i32 s7, 0x2400
	v_add3_u32 v0, v198, s7, v200
	v_cvt_pk_bf16_f32 v166, v246, v202
	v_cvt_pk_bf16_f32 v167, v203, v204
	v_cvt_pk_bf16_f32 v168, v205, v206
	v_cvt_pk_bf16_f32 v169, v207, v208
	v_exp_f32_e32 v209, v58
	v_exp_f32_e32 v210, v59
	s_waitcnt lgkmcnt(4)
	v_mfma_f32_32x32x16_bf16 v[18:33], v[238:241], v[166:169], v[18:33]
	ds_read_b128 v[238:241], v247 offset:57920
	s_waitcnt lgkmcnt(4)
	v_mfma_f32_32x32x16_bf16 v[2:17], v[242:245], v[166:169], v[2:17]
	ds_read_b128 v[242:245], v247 offset:53344
	v_cvt_pk_bf16_f32 v162, v209, v210
	v_cvt_pk_bf16_f32 v163, v211, v212
	v_cvt_pk_bf16_f32 v164, v213, v214
	v_cvt_pk_bf16_f32 v165, v215, v216
	v_exp_f32_e32 v217, v66
	v_exp_f32_e32 v218, v67
	s_waitcnt lgkmcnt(4)
	v_mfma_f32_32x32x16_bf16 v[18:33], v[226:229], v[162:165], v[18:33]
	ds_read_b128 v[226:229], v247 offset:57952
	v_exp_f32_e32 v219, v68
	v_exp_f32_e32 v220, v69
	v_exp_f32_e32 v221, v70
	v_exp_f32_e32 v222, v71
	v_exp_f32_e32 v223, v72
	v_exp_f32_e32 v224, v73
	v_cvt_pk_bf16_f32 v70, v217, v218
	s_waitcnt lgkmcnt(4)
	v_mfma_f32_32x32x16_bf16 v[2:17], v[230:233], v[162:165], v[2:17]
	ds_read_b128 v[230:233], v0 offset:53248
	v_cvt_pk_bf16_f32 v71, v219, v220
	v_cvt_pk_bf16_f32 v72, v221, v222
	v_cvt_pk_bf16_f32 v73, v223, v224
	v_exp_f32_e32 v74, v74
	v_exp_f32_e32 v75, v75
	v_exp_f32_e32 v76, v76
	s_waitcnt lgkmcnt(4)
	v_mfma_f32_32x32x16_bf16 v[18:33], v[234:237], v[70:73], v[18:33]
	ds_read_b128 v[234:237], v0 offset:57856
	v_exp_f32_e32 v77, v77
	v_exp_f32_e32 v78, v78
	v_exp_f32_e32 v79, v79
	v_exp_f32_e32 v80, v80
	v_exp_f32_e32 v81, v81
	v_cvt_pk_bf16_f32 v66, v74, v75
	s_waitcnt lgkmcnt(4)
	v_mfma_f32_32x32x16_bf16 v[2:17], v[238:241], v[70:73], v[2:17]
	ds_read_b128 v[238:241], v0 offset:53280
	v_cvt_pk_bf16_f32 v67, v76, v77
	v_cvt_pk_bf16_f32 v68, v78, v79
	v_cvt_pk_bf16_f32 v69, v80, v81
	v_exp_f32_e32 v82, v82
	v_exp_f32_e32 v83, v83
	s_waitcnt lgkmcnt(4)
	v_mfma_f32_32x32x16_bf16 v[18:33], v[242:245], v[66:69], v[18:33]
	ds_read_b128 v[242:245], v0 offset:57888
	v_exp_f32_e32 v84, v84
	v_exp_f32_e32 v85, v85
	v_exp_f32_e32 v86, v86
	v_exp_f32_e32 v87, v87
	v_exp_f32_e32 v88, v88
	v_exp_f32_e32 v89, v89
	s_waitcnt lgkmcnt(4)
	v_mfma_f32_32x32x16_bf16 v[2:17], v[226:229], v[66:69], v[2:17]
	ds_read_b128 v[226:229], v0 offset:53312
	v_cvt_pk_bf16_f32 v62, v82, v83
	v_cvt_pk_bf16_f32 v63, v84, v85
	v_cvt_pk_bf16_f32 v64, v86, v87
	v_cvt_pk_bf16_f32 v65, v88, v89
	v_exp_f32_e32 v90, v90
	v_exp_f32_e32 v91, v91
	s_waitcnt lgkmcnt(4)
	v_mfma_f32_32x32x16_bf16 v[18:33], v[230:233], v[62:65], v[18:33]
	ds_read_b128 v[230:233], v0 offset:57920
	v_exp_f32_e32 v92, v92
	v_exp_f32_e32 v93, v93
	v_exp_f32_e32 v94, v94
	v_exp_f32_e32 v95, v95
	v_exp_f32_e32 v96, v96
	v_exp_f32_e32 v97, v97
	s_waitcnt lgkmcnt(4)
	v_mfma_f32_32x32x16_bf16 v[2:17], v[234:237], v[62:65], v[2:17]
	ds_read_b128 v[234:237], v0 offset:53344
	v_cvt_pk_bf16_f32 v58, v90, v91
	v_cvt_pk_bf16_f32 v59, v92, v93
	v_cvt_pk_bf16_f32 v60, v94, v95
	v_cvt_pk_bf16_f32 v61, v96, v97
	v_exp_f32_e32 v98, v98
	v_exp_f32_e32 v99, v99
	s_waitcnt lgkmcnt(4)
	v_mfma_f32_32x32x16_bf16 v[18:33], v[238:241], v[58:61], v[18:33]
	ds_read_b128 v[238:241], v0 offset:57952
	v_exp_f32_e32 v100, v100
	v_exp_f32_e32 v101, v101
	v_exp_f32_e32 v102, v102
	v_exp_f32_e32 v103, v103
	v_exp_f32_e32 v104, v104
	v_exp_f32_e32 v105, v105
	v_cvt_pk_bf16_f32 v54, v98, v99
	s_waitcnt lgkmcnt(4)
	v_mfma_f32_32x32x16_bf16 v[2:17], v[242:245], v[58:61], v[2:17]
	v_cvt_pk_bf16_f32 v55, v100, v101
	v_cvt_pk_bf16_f32 v56, v102, v103
	v_cvt_pk_bf16_f32 v57, v104, v105
	v_exp_f32_e32 v106, v106
	v_exp_f32_e32 v107, v107
	v_exp_f32_e32 v108, v108
	s_waitcnt lgkmcnt(3)
	v_mfma_f32_32x32x16_bf16 v[18:33], v[226:229], v[54:57], v[18:33]
	v_exp_f32_e32 v109, v109
	v_exp_f32_e32 v110, v110
	v_exp_f32_e32 v111, v111
	v_exp_f32_e32 v112, v112
	v_exp_f32_e32 v113, v113
	v_cvt_pk_bf16_f32 v50, v106, v107
	s_waitcnt lgkmcnt(2)
	v_mfma_f32_32x32x16_bf16 v[2:17], v[230:233], v[54:57], v[2:17]
	v_cvt_pk_bf16_f32 v51, v108, v109
	v_cvt_pk_bf16_f32 v52, v110, v111
	v_cvt_pk_bf16_f32 v53, v112, v113
	s_add_i32 s15, s14, -2
	s_waitcnt lgkmcnt(1)
	v_mfma_f32_32x32x16_bf16 v[18:33], v[234:237], v[50:53], v[18:33]
	s_waitcnt lgkmcnt(0)
	v_mfma_f32_32x32x16_bf16 v[2:17], v[238:241], v[50:53], v[2:17]
	s_branch .LBB0_299

.LBB0_350:
	v_exp_f32_e32 v166, v98
	v_exp_f32_e32 v167, v99
	v_exp_f32_e32 v168, v100
	v_exp_f32_e32 v169, v101
	v_exp_f32_e32 v170, v102
	v_exp_f32_e32 v171, v103
	v_exp_f32_e32 v172, v104
	v_exp_f32_e32 v173, v105
	v_cvt_pk_bf16_f32 v146, v166, v167
	v_cvt_pk_bf16_f32 v147, v168, v169
	v_cvt_pk_bf16_f32 v148, v170, v171
	v_cvt_pk_bf16_f32 v149, v172, v173
	v_exp_f32_e32 v106, v106
	v_exp_f32_e32 v107, v107
	s_waitcnt lgkmcnt(5)
	v_mfma_f32_32x32x16_bf16 v[18:33], v[206:209], v[146:149], v[18:33]
	ds_read_b128 v[206:209], v0 offset:36960
	v_exp_f32_e32 v108, v108
	v_exp_f32_e32 v109, v109
	v_exp_f32_e32 v110, v110
	v_exp_f32_e32 v111, v111
	v_exp_f32_e32 v112, v112
	v_exp_f32_e32 v113, v113
	s_waitcnt lgkmcnt(5)
	v_mfma_f32_32x32x16_bf16 v[2:17], v[210:213], v[146:149], v[2:17]
	ds_read_b128 v[210:213], v0 offset:41568
	v_cvt_pk_bf16_f32 v102, v106, v107
	v_cvt_pk_bf16_f32 v103, v108, v109
	v_cvt_pk_bf16_f32 v104, v110, v111
	v_cvt_pk_bf16_f32 v105, v112, v113
	v_exp_f32_e32 v174, v66
	v_exp_f32_e32 v175, v67
	s_waitcnt lgkmcnt(5)
	v_mfma_f32_32x32x16_bf16 v[18:33], v[222:225], v[102:105], v[18:33]
	ds_read_b128 v[222:225], v0 offset:46080
	v_exp_f32_e32 v176, v68
	v_exp_f32_e32 v177, v69
	v_exp_f32_e32 v178, v70
	v_exp_f32_e32 v179, v71
	v_exp_f32_e32 v191, v72
	v_exp_f32_e32 v192, v73
	v_cvt_pk_bf16_f32 v98, v174, v175
	s_waitcnt lgkmcnt(5)
	v_mfma_f32_32x32x16_bf16 v[2:17], v[226:229], v[102:105], v[2:17]
	ds_read_b128 v[226:229], v0 offset:50688
	v_cvt_pk_bf16_f32 v99, v176, v177
	v_cvt_pk_bf16_f32 v100, v178, v179
	v_cvt_pk_bf16_f32 v101, v191, v192
	v_exp_f32_e32 v74, v74
	v_exp_f32_e32 v75, v75
	v_exp_f32_e32 v76, v76
	s_waitcnt lgkmcnt(5)
	v_mfma_f32_32x32x16_bf16 v[18:33], v[230:233], v[98:101], v[18:33]
	ds_read_b128 v[230:233], v0 offset:46112
	v_exp_f32_e32 v77, v77
	v_exp_f32_e32 v78, v78
	v_exp_f32_e32 v79, v79
	v_exp_f32_e32 v80, v80
	v_exp_f32_e32 v81, v81
	v_cvt_pk_bf16_f32 v70, v74, v75
	s_waitcnt lgkmcnt(5)
	v_mfma_f32_32x32x16_bf16 v[2:17], v[234:237], v[98:101], v[2:17]
	ds_read_b128 v[234:237], v0 offset:50720
	v_cvt_pk_bf16_f32 v71, v76, v77
	v_cvt_pk_bf16_f32 v72, v78, v79
	v_cvt_pk_bf16_f32 v73, v80, v81
	v_exp_f32_e32 v193, v50
	v_exp_f32_e32 v194, v51
	v_exp_f32_e32 v195, v52
	s_waitcnt lgkmcnt(5)
	v_mfma_f32_32x32x16_bf16 v[18:33], v[206:209], v[70:73], v[18:33]
	ds_read_b128 v[206:209], v0 offset:46144
	v_cvt_pk_bf16_f32 v66, v193, v194
	s_waitcnt lgkmcnt(5)
	v_mfma_f32_32x32x16_bf16 v[2:17], v[210:213], v[70:73], v[2:17]
	ds_read_b128 v[210:213], v0 offset:50752
	v_cvt_pk_bf16_f32 v67, v195, v196
	v_cvt_pk_bf16_f32 v68, v197, v198
	v_cvt_pk_bf16_f32 v69, v199, v200
	v_exp_f32_e32 v201, v58
	v_exp_f32_e32 v202, v59
	v_exp_f32_e32 v203, v60
	s_waitcnt lgkmcnt(5)
	v_mfma_f32_32x32x16_bf16 v[18:33], v[222:225], v[66:69], v[18:33]
	ds_read_b128 v[222:225], v0 offset:46176
	v_exp_f32_e32 v62, v62
	v_exp_f32_e32 v63, v63
	v_exp_f32_e32 v64, v64
	v_exp_f32_e32 v65, v65
	v_cvt_pk_bf16_f32 v58, v201, v202
	s_waitcnt lgkmcnt(5)
	v_mfma_f32_32x32x16_bf16 v[2:17], v[226:229], v[66:69], v[2:17]
	ds_read_b128 v[226:229], v0 offset:50784
	v_cvt_pk_bf16_f32 v59, v203, v204
	v_cvt_pk_bf16_f32 v60, v62, v63
	v_cvt_pk_bf16_f32 v61, v64, v65
	v_exp_f32_e32 v82, v82
	v_exp_f32_e32 v83, v83
	v_exp_f32_e32 v84, v84
	s_waitcnt lgkmcnt(5)
	v_mfma_f32_32x32x16_bf16 v[18:33], v[230:233], v[58:61], v[18:33]
	v_exp_f32_e32 v85, v85
	v_exp_f32_e32 v86, v86
	v_exp_f32_e32 v87, v87
	v_exp_f32_e32 v88, v88
	v_exp_f32_e32 v89, v89
	v_cvt_pk_bf16_f32 v54, v82, v83
	s_waitcnt lgkmcnt(4)
	v_mfma_f32_32x32x16_bf16 v[2:17], v[234:237], v[58:61], v[2:17]
	v_cvt_pk_bf16_f32 v55, v84, v85
	v_cvt_pk_bf16_f32 v56, v86, v87
	v_cvt_pk_bf16_f32 v57, v88, v89
	v_exp_f32_e32 v90, v90
	v_exp_f32_e32 v91, v91
	v_exp_f32_e32 v92, v92
	s_waitcnt lgkmcnt(3)
	v_mfma_f32_32x32x16_bf16 v[18:33], v[206:209], v[54:57], v[18:33]
	v_exp_f32_e32 v93, v93
	v_exp_f32_e32 v94, v94
	v_exp_f32_e32 v95, v95
	v_exp_f32_e32 v96, v96
	v_exp_f32_e32 v97, v97
	v_cvt_pk_bf16_f32 v50, v90, v91
	s_waitcnt lgkmcnt(2)
	v_mfma_f32_32x32x16_bf16 v[2:17], v[210:213], v[54:57], v[2:17]
	v_cvt_pk_bf16_f32 v51, v92, v93
	v_cvt_pk_bf16_f32 v52, v94, v95
	v_cvt_pk_bf16_f32 v53, v96, v97
	s_add_i32 s13, s12, -2
	s_waitcnt lgkmcnt(1)
	v_mfma_f32_32x32x16_bf16 v[18:33], v[222:225], v[50:53], v[18:33]
	s_waitcnt lgkmcnt(0)
	v_mfma_f32_32x32x16_bf16 v[2:17], v[226:229], v[50:53], v[2:17]
	s_branch .LBB0_347

.LBB0_387:
	s_mul_i32 s71, s70, 0xa0
	v_or_b32_e32 v0, s71, v109
	v_mul_hi_u32 v34, v0, s51
	v_lshrrev_b32_e32 v34, 5, v34
	v_mul_i32_i24_e32 v35, 0xffffffd8, v34
	v_add_lshl_u32 v34, v34, v111, 6
	v_add_u32_e32 v0, v0, v112
	v_add3_u32 v34, v0, v35, v34
	v_ashrrev_i32_e32 v35, 31, v34
	v_lshlrev_b64 v[34:35], 9, v[34:35]
	v_lshl_add_u64 v[38:39], v[98:99], 0, v[34:35]
	global_load_dwordx4 v[34:37], v[38:39], off
	global_load_dwordx4 v[90:93], v[38:39], off offset:32
	global_load_dwordx4 v[86:89], v[38:39], off offset:64
	global_load_dwordx4 v[82:85], v[38:39], off offset:96
	s_mul_i32 s64, s70, 0x1f0
	v_or_b32_e32 v38, s71, v118
	v_add_u32_e32 v120, s64, v119
	s_mul_i32 s64, s70, 0x8020
	v_mul_hi_u32 v0, v38, s51
	s_bfe_u32 s64, s64, 0x3000d
	v_lshrrev_b32_e32 v0, 5, v0
	v_add_u32_e32 v39, s64, v111
	v_add_lshl_u32 v40, v0, v111, 12
	v_mul_i32_i24_e32 v42, 0xffffffd8, v0
	v_add_u32_e32 v0, v38, v104
	v_lshlrev_b32_e32 v122, 1, v113
	v_add3_u32 v44, v0, v42, v40
	v_lshl_or_b32 v0, v39, 13, v122
	v_lshl_add_u64 v[46:47], v[100:101], 0, v[0:1]
	global_load_dwordx2 v[74:75], v[46:47], off
	v_or_b32_e32 v46, s71, v110
	v_mov_b32_e32 v47, v1
	v_ashrrev_i32_e32 v43, 31, v42
	v_lshl_add_u64 v[46:47], v[46:47], 0, v[104:105]
	v_mov_b32_e32 v41, v1
	v_lshl_add_u64 v[42:43], v[46:47], 0, v[42:43]
	v_lshl_add_u64 v[40:41], v[42:43], 0, v[40:41]
	v_lshl_add_u64 v[40:41], v[40:41], 1, v[100:101]
	s_or_b32 s64, s71, 16
	global_load_dwordx2 v[76:77], v[40:41], off offset:16
	v_lshl_add_u64 v[40:41], v[102:103], 0, v[0:1]
	v_or_b32_e32 v0, s64, v118
	v_ashrrev_i32_e32 v45, 31, v44
	v_mul_hi_u32 v39, v0, s51
	global_load_dwordx2 v[66:67], v[40:41], off
	v_lshl_add_u64 v[40:41], v[44:45], 1, v[102:103]
	s_mulk_i32 s64, 0xcd
	v_lshrrev_b32_e32 v39, 5, v39
	global_load_dwordx2 v[68:69], v[40:41], off
	s_bfe_u32 s64, s64, 0x3000d
	v_add_lshl_u32 v40, v39, v111, 12
	v_mul_i32_i24_e32 v42, 0xffffffd8, v39
	v_mov_b32_e32 v39, v1
	v_add_lshl_u32 v41, v111, s64, 12
	v_add_u32_e32 v0, v0, v104
	v_ashrrev_i32_e32 v43, 31, v42
	v_lshl_add_u64 v[106:107], v[38:39], 0, v[104:105]
	v_or_b32_e32 v48, v41, v117
	v_add3_u32 v44, v0, v42, v40
	v_or_b32_e32 v0, v41, v113
	v_mov_b32_e32 v41, v1
	v_lshl_add_u64 v[38:39], v[106:107], 0, v[42:43]
	v_lshlrev_b32_e32 v0, 1, v0
	v_lshl_add_u64 v[38:39], v[38:39], 0, v[40:41]
	v_lshl_add_u64 v[46:47], v[100:101], 0, v[0:1]
	v_lshl_add_u64 v[38:39], v[38:39], 1, v[100:101]
	v_lshlrev_b32_e32 v0, 1, v48
	v_ashrrev_i32_e32 v45, 31, v44
	global_load_dwordx2 v[72:73], v[38:39], off offset:32
	v_lshl_add_u64 v[38:39], v[102:103], 0, v[0:1]
	global_load_dwordx2 v[70:71], v[46:47], off offset:32
	global_load_dwordx2 v[78:79], v[38:39], off
	v_lshl_add_u64 v[38:39], v[44:45], 1, v[102:103]
	global_load_dwordx2 v[80:81], v[38:39], off
	v_mov_b32_e32 v0, 0xff800000
	s_waitcnt vmcnt(11)
	v_mfma_f32_32x32x16_bf16 v[34:49], v[34:37], v[50:53], 0
	s_waitcnt vmcnt(10)
	v_mfma_f32_32x32x16_bf16 v[34:49], v[90:93], v[54:57], v[34:49]
	s_waitcnt vmcnt(9)
	v_mfma_f32_32x32x16_bf16 v[34:49], v[86:89], v[58:61], v[34:49]
	s_waitcnt vmcnt(8)
	v_mfma_f32_32x32x16_bf16 v[34:49], v[82:85], v[62:65], v[34:49]
	v_mov_b32_e32 v218, 0xff800000
	ds_read_b32 v202, v120 offset:928
	ds_read_b32 v203, v120 offset:932
	ds_read_b32 v204, v120 offset:936
	ds_read_b32 v205, v120 offset:940
	ds_read_b32 v206, v120 offset:960
	ds_read_b32 v207, v120 offset:964
	ds_read_b32 v208, v120 offset:968
	ds_read_b32 v209, v120 offset:972
	ds_read_b32 v210, v120 offset:992
	ds_read_b32 v211, v120 offset:996
	ds_read_b32 v212, v120 offset:1000
	ds_read_b32 v213, v120 offset:1004
	ds_read_b32 v214, v120 offset:1024
	ds_read_b32 v215, v120 offset:1028
	ds_read_b32 v216, v120 offset:1032
	ds_read_b32 v217, v120 offset:1036
	s_waitcnt lgkmcnt(0)
	v_add_f32_e32 v202, v34, v202
	v_add_f32_e32 v203, v35, v203
	v_add_f32_e32 v204, v36, v204
	v_add_f32_e32 v205, v37, v205
	v_add_f32_e32 v206, v38, v206
	v_add_f32_e32 v207, v39, v207
	v_add_f32_e32 v208, v40, v208
	v_add_f32_e32 v209, v41, v209
	v_add_f32_e32 v210, v42, v210
	v_add_f32_e32 v211, v43, v211
	v_add_f32_e32 v212, v44, v212
	v_add_f32_e32 v213, v45, v213
	v_add_f32_e32 v214, v46, v214
	v_add_f32_e32 v215, v47, v215
	v_add_f32_e32 v216, v48, v216
	v_add_f32_e32 v217, v49, v217
	v_cndmask_b32_e64 v82, v218, v202, s[0:1]
	v_cndmask_b32_e64 v0, v218, v203, s[4:5]
	v_cndmask_b32_e64 v35, v218, v204, s[6:7]
	v_cndmask_b32_e64 v34, v218, v205, s[8:9]
	v_cndmask_b32_e64 v86, v218, v206, s[10:11]
	v_cndmask_b32_e64 v37, v218, v207, s[12:13]
	v_cndmask_b32_e64 v88, v218, v208, s[14:15]
	v_cndmask_b32_e64 v89, v218, v209, s[16:17]
	v_cndmask_b32_e64 v90, v218, v210, s[18:19]
	v_cndmask_b32_e64 v41, v218, v211, s[20:21]
	v_cndmask_b32_e64 v43, v218, v212, s[22:23]
	v_cndmask_b32_e64 v42, v218, v213, s[24:25]
	v_cndmask_b32_e64 v38, v218, v214, s[26:27]
	v_cndmask_b32_e64 v36, v218, v215, s[28:29]
	v_cndmask_b32_e64 v40, v218, v216, s[30:31]
	v_cndmask_b32_e64 v39, v218, v217, s[34:35]
	s_mov_b32 s64, 0xff800000
	v_max3_f32 v44, v82, s64, v0
	v_max3_f32 v44, v44, v35, v34
	v_max3_f32 v44, v44, v86, v37
	v_max3_f32 v44, v44, v88, v89
	v_max3_f32 v44, v44, v90, v41
	v_max3_f32 v44, v44, v43, v42
	v_max3_f32 v44, v44, v38, v36
	v_max3_f32 v44, v44, v40, v39
	v_mov_b32_e32 v45, v44
	s_nop 1
	v_permlane32_swap_b32_e32 v44, v45
	v_max_f32_e32 v45, v45, v45
	v_max_f32_e32 v44, v44, v44
	v_max_f32_e32 v44, v44, v45
	v_sub_f32_e32 v45, v44, v121
	v_cmp_lt_f32_e32 vcc, s50, v45
	s_cbranch_vccz .LBB0_421
	v_max_f32_e32 v44, v44, v44
	v_max_f32_e32 v45, v121, v121
	v_max_f32_e32 v45, v45, v44
	v_sub_f32_e32 v44, v121, v45
	v_exp_f32_e32 v44, v44
	v_mov_b32_e32 v121, v45
	v_pk_mul_f32 v[32:33], v[32:33], v[44:45] op_sel_hi:[1,0]
	v_pk_mul_f32 v[30:31], v[30:31], v[44:45] op_sel_hi:[1,0]
	v_pk_mul_f32 v[28:29], v[28:29], v[44:45] op_sel_hi:[1,0]
	v_pk_mul_f32 v[26:27], v[26:27], v[44:45] op_sel_hi:[1,0]
	v_pk_mul_f32 v[24:25], v[24:25], v[44:45] op_sel_hi:[1,0]
	v_pk_mul_f32 v[22:23], v[22:23], v[44:45] op_sel_hi:[1,0]
	v_pk_mul_f32 v[20:21], v[20:21], v[44:45] op_sel_hi:[1,0]
	v_pk_mul_f32 v[18:19], v[18:19], v[44:45] op_sel_hi:[1,0]
	v_pk_mul_f32 v[16:17], v[16:17], v[44:45] op_sel_hi:[1,0]
	v_pk_mul_f32 v[14:15], v[14:15], v[44:45] op_sel_hi:[1,0]
	v_pk_mul_f32 v[12:13], v[12:13], v[44:45] op_sel_hi:[1,0]
	v_pk_mul_f32 v[10:11], v[10:11], v[44:45] op_sel_hi:[1,0]
	v_pk_mul_f32 v[8:9], v[8:9], v[44:45] op_sel_hi:[1,0]
	v_pk_mul_f32 v[6:7], v[6:7], v[44:45] op_sel_hi:[1,0]
	v_pk_mul_f32 v[4:5], v[4:5], v[44:45] op_sel_hi:[1,0]
	v_pk_mul_f32 v[2:3], v[2:3], v[44:45] op_sel_hi:[1,0]
	v_mul_f32_e32 v123, v123, v44
